# cross prompt unit QK^T: K fragments streamed through rotating registers with counted lgkmcnt (on top of previous)
# speedup vs baseline: 1.0020x; 1.0020x over previous
.LBB0_179:
	s_andn2_b64 vcc, exec, s[6:7]
	s_cbranch_vccnz .LBB0_150
	s_andn2_b64 vcc, exec, s[18:19]
	s_cbranch_vccnz .LBB0_150
	s_ashr_i32 s0, s24, 7
	s_lshl_b32 s7, s24, 4
	s_lshl_b32 s6, s0, 11
	s_and_b32 s7, s7, 0x780
	s_or_b32 s6, s6, s7
	v_add_u32_e32 v0, s6, v176
	s_lshl_b32 s6, s0, 8
	s_ashr_i32 s7, s6, 31
	s_mov_b64 s[20:21], s[94:95]
	s_lshl_b64 s[6:7], s[6:7], 12
	s_add_u32 s0, s20, s53
	s_addc_u32 s22, s21, 0
	s_add_u32 s6, s0, s6
	s_addc_u32 s7, s22, s7
	s_lshl_b32 s0, s24, 8
	s_and_b32 s0, s0, 0x600
	v_ashrrev_i32_e32 v1, 31, v0
	s_add_u32 s6, s6, s0
	v_lshlrev_b64 v[0:1], 11, v[0:1]
	s_addc_u32 s7, s7, 0
	v_lshl_add_u64 v[0:1], s[20:21], 0, v[0:1]
	s_add_u32 s6, s6, 0x5100000
	v_lshlrev_b32_e32 v152, 1, v96
	v_lshl_add_u64 v[52:53], v[0:1], 0, s[0:1]
	s_addc_u32 s7, s7, 0
	v_lshl_add_u64 v[0:1], v[52:53], 0, v[152:153]
	s_mov_b64 s[20:21], 0x1b500000
	s_mov_b32 s0, 0x1b500000
	v_lshl_add_u64 v[2:3], v[0:1], 0, s[20:21]
	v_add_co_u32_e32 v0, vcc, s0, v0
	v_lshl_add_u64 v[32:33], s[6:7], 0, v[100:101]
	s_nop 0
	v_addc_co_u32_e32 v1, vcc, 0, v1, vcc
	v_lshl_add_u64 v[32:33], v[102:103], 1, v[32:33]
	flat_load_dwordx4 v[28:31], v[0:1]
	flat_load_dwordx4 v[24:27], v[2:3] offset:64
	flat_load_dwordx4 v[20:23], v[2:3] offset:128
	flat_load_dwordx4 v[16:19], v[2:3] offset:192
	flat_load_dwordx4 v[12:15], v[2:3] offset:256
	flat_load_dwordx4 v[8:11], v[2:3] offset:320
	flat_load_dwordx4 v[4:7], v[2:3] offset:384
	s_nop 0
	flat_load_dwordx4 v[0:3], v[2:3] offset:448
	s_nop 0
	v_lshl_add_u64 v[34:35], s[6:7], 0, v[104:105]
	v_lshl_add_u64 v[34:35], v[106:107], 1, v[34:35]
	v_lshl_add_u64 v[36:37], s[6:7], 0, v[108:109]
	v_lshl_add_u64 v[36:37], v[110:111], 1, v[36:37]
	v_lshl_add_u64 v[38:39], s[6:7], 0, v[112:113]
	v_lshl_add_u64 v[38:39], v[114:115], 1, v[38:39]
	v_lshl_add_u64 v[40:41], s[6:7], 0, v[116:117]
	v_lshl_add_u64 v[40:41], v[118:119], 1, v[40:41]
	v_lshl_add_u64 v[42:43], s[6:7], 0, v[120:121]
	v_lshl_add_u64 v[42:43], v[122:123], 1, v[42:43]
	v_lshl_add_u64 v[44:45], s[6:7], 0, v[124:125]
	v_lshl_add_u64 v[44:45], v[126:127], 1, v[44:45]
	v_lshl_add_u64 v[46:47], s[6:7], 0, v[128:129]
	v_lshl_add_u64 v[46:47], v[130:131], 1, v[46:47]
	global_load_dwordx4 v[224:227], v[32:33], off
	global_load_dwordx4 v[228:231], v[34:35], off
	global_load_dwordx4 v[232:235], v[36:37], off
	global_load_dwordx4 v[236:239], v[38:39], off
	global_load_dwordx4 v[240:243], v[40:41], off
	global_load_dwordx4 v[244:247], v[42:43], off
	global_load_dwordx4 v[248:251], v[44:45], off
	global_load_dwordx4 v[48:51], v[46:47], off
	s_waitcnt vmcnt(0) lgkmcnt(0)
	ds_write_b128 v195, v[224:227]
	ds_write_b128 v196, v[228:231]
	ds_write_b128 v197, v[232:235]
	ds_write_b128 v198, v[236:239]
	ds_write_b128 v199, v[240:243]
	ds_write_b128 v200, v[244:247]
	ds_write_b128 v201, v[248:251]
	ds_write_b128 v202, v[48:51]
	s_waitcnt lgkmcnt(0)
	s_barrier
	ds_read_b128 v[224:227], v203
	ds_read_b128 v[228:231], v203 offset:4352
	ds_read_b128 v[232:235], v203 offset:8704
	ds_read_b128 v[236:239], v204
	ds_read_b128 v[240:243], v203 offset:17408
	ds_read_b128 v[244:247], v203 offset:21760
	ds_read_b128 v[248:251], v203 offset:26112
	s_waitcnt lgkmcnt(6)
	v_mfma_f32_16x16x32_bf16 v[90:93], v[224:227], v[28:31], 0
	ds_read_b128 v[224:227], v205
	s_waitcnt lgkmcnt(6)
	v_mfma_f32_16x16x32_bf16 v[162:165], v[228:231], v[28:31], 0
	ds_read_b128 v[228:231], v203 offset:34816
	s_waitcnt lgkmcnt(6)
	v_mfma_f32_16x16x32_bf16 v[166:169], v[232:235], v[28:31], 0
	ds_read_b128 v[232:235], v203 offset:39168
	s_waitcnt lgkmcnt(6)
	v_mfma_f32_16x16x32_bf16 v[48:51], v[236:239], v[28:31], 0
	ds_read_b128 v[236:239], v203 offset:43520
	s_waitcnt lgkmcnt(6)
	v_mfma_f32_16x16x32_bf16 v[54:57], v[240:243], v[28:31], 0
	ds_read_b128 v[240:243], v206
	s_waitcnt lgkmcnt(6)
	v_mfma_f32_16x16x32_bf16 v[58:61], v[244:247], v[28:31], 0
	ds_read_b128 v[244:247], v203 offset:52224
	s_waitcnt lgkmcnt(6)
	v_mfma_f32_16x16x32_bf16 v[62:65], v[248:251], v[28:31], 0
	ds_read_b128 v[248:251], v203 offset:56576
	s_waitcnt lgkmcnt(6)
	v_mfma_f32_16x16x32_bf16 v[66:69], v[224:227], v[28:31], 0
	ds_read_b128 v[224:227], v203 offset:60928
	s_waitcnt lgkmcnt(6)
	v_mfma_f32_16x16x32_bf16 v[70:73], v[228:231], v[28:31], 0
	ds_read_b128 v[228:231], v207
	s_waitcnt lgkmcnt(6)
	v_mfma_f32_16x16x32_bf16 v[74:77], v[232:235], v[28:31], 0
	ds_read_b128 v[232:235], v203 offset:64
	s_waitcnt lgkmcnt(6)
	v_mfma_f32_16x16x32_bf16 v[78:81], v[236:239], v[28:31], 0
	ds_read_b128 v[236:239], v203 offset:4416
	s_waitcnt lgkmcnt(6)
	v_mfma_f32_16x16x32_bf16 v[82:85], v[240:243], v[28:31], 0
	ds_read_b128 v[240:243], v203 offset:8768
	s_waitcnt lgkmcnt(6)
	v_mfma_f32_16x16x32_bf16 v[86:89], v[244:247], v[28:31], 0
	ds_read_b128 v[244:247], v204 offset:64
	s_waitcnt lgkmcnt(6)
	v_mfma_f32_16x16x32_bf16 v[170:173], v[248:251], v[28:31], 0
	ds_read_b128 v[248:251], v203 offset:17472
	s_waitcnt lgkmcnt(6)
	v_mfma_f32_16x16x32_bf16 v[216:219], v[224:227], v[28:31], 0
	ds_read_b128 v[224:227], v203 offset:21824
	s_waitcnt lgkmcnt(6)
	v_mfma_f32_16x16x32_bf16 v[220:223], v[228:231], v[28:31], 0
	ds_read_b128 v[228:231], v203 offset:26176
	s_waitcnt lgkmcnt(6)
	v_mfma_f32_16x16x32_bf16 v[90:93], v[232:235], v[24:27], v[90:93]
	ds_read_b128 v[232:235], v205 offset:64
	s_waitcnt lgkmcnt(6)
	v_mfma_f32_16x16x32_bf16 v[162:165], v[236:239], v[24:27], v[162:165]
	ds_read_b128 v[236:239], v203 offset:34880
	s_waitcnt lgkmcnt(6)
	v_mfma_f32_16x16x32_bf16 v[166:169], v[240:243], v[24:27], v[166:169]
	ds_read_b128 v[240:243], v203 offset:39232
	s_waitcnt lgkmcnt(6)
	v_mfma_f32_16x16x32_bf16 v[48:51], v[244:247], v[24:27], v[48:51]
	ds_read_b128 v[244:247], v203 offset:43584
	s_waitcnt lgkmcnt(6)
	v_mfma_f32_16x16x32_bf16 v[54:57], v[248:251], v[24:27], v[54:57]
	ds_read_b128 v[248:251], v206 offset:64
	s_waitcnt lgkmcnt(6)
	v_mfma_f32_16x16x32_bf16 v[58:61], v[224:227], v[24:27], v[58:61]
	ds_read_b128 v[224:227], v203 offset:52288
	s_waitcnt lgkmcnt(6)
	v_mfma_f32_16x16x32_bf16 v[62:65], v[228:231], v[24:27], v[62:65]
	ds_read_b128 v[228:231], v203 offset:56640
	s_waitcnt lgkmcnt(6)
	v_mfma_f32_16x16x32_bf16 v[66:69], v[232:235], v[24:27], v[66:69]
	ds_read_b128 v[232:235], v203 offset:60992
	s_waitcnt lgkmcnt(6)
	v_mfma_f32_16x16x32_bf16 v[70:73], v[236:239], v[24:27], v[70:73]
	ds_read_b128 v[236:239], v207 offset:64
	s_waitcnt lgkmcnt(6)
	v_mfma_f32_16x16x32_bf16 v[74:77], v[240:243], v[24:27], v[74:77]
	ds_read_b128 v[240:243], v203 offset:128
	s_waitcnt lgkmcnt(6)
	v_mfma_f32_16x16x32_bf16 v[78:81], v[244:247], v[24:27], v[78:81]
	ds_read_b128 v[244:247], v203 offset:4480
	s_waitcnt lgkmcnt(6)
	v_mfma_f32_16x16x32_bf16 v[82:85], v[248:251], v[24:27], v[82:85]
	ds_read_b128 v[248:251], v203 offset:8832
	s_waitcnt lgkmcnt(6)
	v_mfma_f32_16x16x32_bf16 v[86:89], v[224:227], v[24:27], v[86:89]
	ds_read_b128 v[224:227], v204 offset:128
	s_waitcnt lgkmcnt(6)
	v_mfma_f32_16x16x32_bf16 v[170:173], v[228:231], v[24:27], v[170:173]
	ds_read_b128 v[228:231], v203 offset:17536
	s_waitcnt lgkmcnt(6)
	v_mfma_f32_16x16x32_bf16 v[216:219], v[232:235], v[24:27], v[216:219]
	ds_read_b128 v[232:235], v203 offset:21888
	s_waitcnt lgkmcnt(6)
	v_mfma_f32_16x16x32_bf16 v[220:223], v[236:239], v[24:27], v[220:223]
	ds_read_b128 v[236:239], v203 offset:26240
	s_waitcnt lgkmcnt(6)
	v_mfma_f32_16x16x32_bf16 v[90:93], v[240:243], v[20:23], v[90:93]
	ds_read_b128 v[240:243], v205 offset:128
	s_waitcnt lgkmcnt(6)
	v_mfma_f32_16x16x32_bf16 v[162:165], v[244:247], v[20:23], v[162:165]
	ds_read_b128 v[244:247], v203 offset:34944
	s_waitcnt lgkmcnt(6)
	v_mfma_f32_16x16x32_bf16 v[166:169], v[248:251], v[20:23], v[166:169]
	ds_read_b128 v[248:251], v203 offset:39296
	s_waitcnt lgkmcnt(6)
	v_mfma_f32_16x16x32_bf16 v[48:51], v[224:227], v[20:23], v[48:51]
	ds_read_b128 v[224:227], v203 offset:43648
	s_waitcnt lgkmcnt(6)
	v_mfma_f32_16x16x32_bf16 v[54:57], v[228:231], v[20:23], v[54:57]
	ds_read_b128 v[228:231], v206 offset:128
	s_waitcnt lgkmcnt(6)
	v_mfma_f32_16x16x32_bf16 v[58:61], v[232:235], v[20:23], v[58:61]
	ds_read_b128 v[232:235], v203 offset:52352
	s_waitcnt lgkmcnt(6)
	v_mfma_f32_16x16x32_bf16 v[62:65], v[236:239], v[20:23], v[62:65]
	ds_read_b128 v[236:239], v203 offset:56704
	s_waitcnt lgkmcnt(6)
	v_mfma_f32_16x16x32_bf16 v[66:69], v[240:243], v[20:23], v[66:69]
	ds_read_b128 v[240:243], v203 offset:61056
	s_waitcnt lgkmcnt(6)
	v_mfma_f32_16x16x32_bf16 v[70:73], v[244:247], v[20:23], v[70:73]
	ds_read_b128 v[244:247], v207 offset:128
	s_waitcnt lgkmcnt(6)
	v_mfma_f32_16x16x32_bf16 v[74:77], v[248:251], v[20:23], v[74:77]
	ds_read_b128 v[248:251], v203 offset:192
	s_waitcnt lgkmcnt(6)
	v_mfma_f32_16x16x32_bf16 v[78:81], v[224:227], v[20:23], v[78:81]
	ds_read_b128 v[224:227], v203 offset:4544
	s_waitcnt lgkmcnt(6)
	v_mfma_f32_16x16x32_bf16 v[82:85], v[228:231], v[20:23], v[82:85]
	ds_read_b128 v[228:231], v203 offset:8896
	s_waitcnt lgkmcnt(6)
	v_mfma_f32_16x16x32_bf16 v[86:89], v[232:235], v[20:23], v[86:89]
	ds_read_b128 v[232:235], v204 offset:192
	s_waitcnt lgkmcnt(6)
	v_mfma_f32_16x16x32_bf16 v[170:173], v[236:239], v[20:23], v[170:173]
	ds_read_b128 v[236:239], v203 offset:17600
	s_waitcnt lgkmcnt(6)
	v_mfma_f32_16x16x32_bf16 v[216:219], v[240:243], v[20:23], v[216:219]
	ds_read_b128 v[240:243], v203 offset:21952
	s_waitcnt lgkmcnt(6)
	v_mfma_f32_16x16x32_bf16 v[220:223], v[244:247], v[20:23], v[220:223]
	ds_read_b128 v[244:247], v203 offset:26304
	s_waitcnt lgkmcnt(6)
	v_mfma_f32_16x16x32_bf16 v[90:93], v[248:251], v[16:19], v[90:93]
	ds_read_b128 v[248:251], v205 offset:192
	s_waitcnt lgkmcnt(6)
	v_mfma_f32_16x16x32_bf16 v[162:165], v[224:227], v[16:19], v[162:165]
	ds_read_b128 v[224:227], v203 offset:35008
	s_waitcnt lgkmcnt(6)
	v_mfma_f32_16x16x32_bf16 v[166:169], v[228:231], v[16:19], v[166:169]
	ds_read_b128 v[228:231], v203 offset:39360
	s_waitcnt lgkmcnt(6)
	v_mfma_f32_16x16x32_bf16 v[48:51], v[232:235], v[16:19], v[48:51]
	ds_read_b128 v[232:235], v203 offset:43712
	s_waitcnt lgkmcnt(6)
	v_mfma_f32_16x16x32_bf16 v[54:57], v[236:239], v[16:19], v[54:57]
	ds_read_b128 v[236:239], v206 offset:192
	s_waitcnt lgkmcnt(6)
	v_mfma_f32_16x16x32_bf16 v[58:61], v[240:243], v[16:19], v[58:61]
	ds_read_b128 v[240:243], v203 offset:52416
	s_waitcnt lgkmcnt(6)
	v_mfma_f32_16x16x32_bf16 v[62:65], v[244:247], v[16:19], v[62:65]
	ds_read_b128 v[244:247], v203 offset:56768
	s_waitcnt lgkmcnt(6)
	v_mfma_f32_16x16x32_bf16 v[66:69], v[248:251], v[16:19], v[66:69]
	ds_read_b128 v[248:251], v203 offset:61120
	s_waitcnt lgkmcnt(6)
	v_mfma_f32_16x16x32_bf16 v[70:73], v[224:227], v[16:19], v[70:73]
	ds_read_b128 v[224:227], v207 offset:192
	s_waitcnt lgkmcnt(6)
	v_mfma_f32_16x16x32_bf16 v[74:77], v[228:231], v[16:19], v[74:77]
	s_waitcnt lgkmcnt(5)
	v_mfma_f32_16x16x32_bf16 v[78:81], v[232:235], v[16:19], v[78:81]
	s_waitcnt lgkmcnt(4)
	v_mfma_f32_16x16x32_bf16 v[82:85], v[236:239], v[16:19], v[82:85]
	s_waitcnt lgkmcnt(3)
	v_mfma_f32_16x16x32_bf16 v[86:89], v[240:243], v[16:19], v[86:89]
	s_waitcnt lgkmcnt(2)
	v_mfma_f32_16x16x32_bf16 v[170:173], v[244:247], v[16:19], v[170:173]
	s_waitcnt lgkmcnt(1)
	v_mfma_f32_16x16x32_bf16 v[216:219], v[248:251], v[16:19], v[216:219]
	s_waitcnt lgkmcnt(0)
	v_mfma_f32_16x16x32_bf16 v[220:223], v[224:227], v[16:19], v[220:223]
	s_barrier
	s_nop 1
	global_load_dwordx4 v[224:227], v[32:33], off offset:256
	global_load_dwordx4 v[228:231], v[34:35], off offset:256
	global_load_dwordx4 v[232:235], v[36:37], off offset:256
	global_load_dwordx4 v[236:239], v[38:39], off offset:256
	global_load_dwordx4 v[240:243], v[40:41], off offset:256
	global_load_dwordx4 v[244:247], v[42:43], off offset:256
	global_load_dwordx4 v[248:251], v[44:45], off offset:256
	global_load_dwordx4 v[20:23], v[46:47], off offset:256
	s_waitcnt vmcnt(0) lgkmcnt(0)
	ds_write_b128 v195, v[224:227]
	ds_write_b128 v196, v[228:231]
	ds_write_b128 v197, v[232:235]
	ds_write_b128 v198, v[236:239]
	ds_write_b128 v199, v[240:243]
	ds_write_b128 v200, v[244:247]
	ds_write_b128 v201, v[248:251]
	ds_write_b128 v202, v[20:23]
	s_waitcnt lgkmcnt(0)
	s_barrier
	ds_read_b128 v[224:227], v203
	ds_read_b128 v[228:231], v203 offset:4352
	ds_read_b128 v[232:235], v203 offset:8704
	ds_read_b128 v[236:239], v204
	ds_read_b128 v[240:243], v203 offset:17408
	ds_read_b128 v[244:247], v203 offset:21760
	ds_read_b128 v[248:251], v203 offset:26112
	s_waitcnt lgkmcnt(6)
	v_mfma_f32_16x16x32_bf16 v[90:93], v[224:227], v[12:15], v[90:93]
	ds_read_b128 v[224:227], v205
	s_waitcnt lgkmcnt(6)
	v_mfma_f32_16x16x32_bf16 v[162:165], v[228:231], v[12:15], v[162:165]
	ds_read_b128 v[228:231], v203 offset:34816
	s_waitcnt lgkmcnt(6)
	v_mfma_f32_16x16x32_bf16 v[166:169], v[232:235], v[12:15], v[166:169]
	ds_read_b128 v[232:235], v203 offset:39168
	s_waitcnt lgkmcnt(6)
	v_mfma_f32_16x16x32_bf16 v[48:51], v[236:239], v[12:15], v[48:51]
	ds_read_b128 v[236:239], v203 offset:43520
	s_waitcnt lgkmcnt(6)
	v_mfma_f32_16x16x32_bf16 v[54:57], v[240:243], v[12:15], v[54:57]
	ds_read_b128 v[240:243], v206
	s_waitcnt lgkmcnt(6)
	v_mfma_f32_16x16x32_bf16 v[58:61], v[244:247], v[12:15], v[58:61]
	ds_read_b128 v[244:247], v203 offset:52224
	s_waitcnt lgkmcnt(6)
	v_mfma_f32_16x16x32_bf16 v[62:65], v[248:251], v[12:15], v[62:65]
	ds_read_b128 v[248:251], v203 offset:56576
	s_waitcnt lgkmcnt(6)
	v_mfma_f32_16x16x32_bf16 v[66:69], v[224:227], v[12:15], v[66:69]
	ds_read_b128 v[224:227], v203 offset:60928
	s_waitcnt lgkmcnt(6)
	v_mfma_f32_16x16x32_bf16 v[70:73], v[228:231], v[12:15], v[70:73]
	ds_read_b128 v[228:231], v207
	s_waitcnt lgkmcnt(6)
	v_mfma_f32_16x16x32_bf16 v[74:77], v[232:235], v[12:15], v[74:77]
	ds_read_b128 v[232:235], v203 offset:64
	s_waitcnt lgkmcnt(6)
	v_mfma_f32_16x16x32_bf16 v[78:81], v[236:239], v[12:15], v[78:81]
	ds_read_b128 v[236:239], v203 offset:4416
	s_waitcnt lgkmcnt(6)
	v_mfma_f32_16x16x32_bf16 v[82:85], v[240:243], v[12:15], v[82:85]
	ds_read_b128 v[240:243], v203 offset:8768
	s_waitcnt lgkmcnt(6)
	v_mfma_f32_16x16x32_bf16 v[86:89], v[244:247], v[12:15], v[86:89]
	ds_read_b128 v[244:247], v204 offset:64
	s_waitcnt lgkmcnt(6)
	v_mfma_f32_16x16x32_bf16 v[170:173], v[248:251], v[12:15], v[170:173]
	ds_read_b128 v[248:251], v203 offset:17472
	s_waitcnt lgkmcnt(6)
	v_mfma_f32_16x16x32_bf16 v[216:219], v[224:227], v[12:15], v[216:219]
	ds_read_b128 v[224:227], v203 offset:21824
	s_waitcnt lgkmcnt(6)
	v_mfma_f32_16x16x32_bf16 v[220:223], v[228:231], v[12:15], v[220:223]
	ds_read_b128 v[228:231], v203 offset:26176
	s_waitcnt lgkmcnt(6)
	v_mfma_f32_16x16x32_bf16 v[90:93], v[232:235], v[8:11], v[90:93]
	ds_read_b128 v[232:235], v205 offset:64
	s_waitcnt lgkmcnt(6)
	v_mfma_f32_16x16x32_bf16 v[162:165], v[236:239], v[8:11], v[162:165]
	ds_read_b128 v[236:239], v203 offset:34880
	s_waitcnt lgkmcnt(6)
	v_mfma_f32_16x16x32_bf16 v[166:169], v[240:243], v[8:11], v[166:169]
	ds_read_b128 v[240:243], v203 offset:39232
	s_waitcnt lgkmcnt(6)
	v_mfma_f32_16x16x32_bf16 v[48:51], v[244:247], v[8:11], v[48:51]
	ds_read_b128 v[244:247], v203 offset:43584
	s_waitcnt lgkmcnt(6)
	v_mfma_f32_16x16x32_bf16 v[54:57], v[248:251], v[8:11], v[54:57]
	ds_read_b128 v[248:251], v206 offset:64
	s_waitcnt lgkmcnt(6)
	v_mfma_f32_16x16x32_bf16 v[58:61], v[224:227], v[8:11], v[58:61]
	ds_read_b128 v[224:227], v203 offset:52288
	s_waitcnt lgkmcnt(6)
	v_mfma_f32_16x16x32_bf16 v[62:65], v[228:231], v[8:11], v[62:65]
	ds_read_b128 v[228:231], v203 offset:56640
	s_waitcnt lgkmcnt(6)
	v_mfma_f32_16x16x32_bf16 v[66:69], v[232:235], v[8:11], v[66:69]
	ds_read_b128 v[232:235], v203 offset:60992
	s_waitcnt lgkmcnt(6)
	v_mfma_f32_16x16x32_bf16 v[70:73], v[236:239], v[8:11], v[70:73]
	ds_read_b128 v[236:239], v207 offset:64
	s_waitcnt lgkmcnt(6)
	v_mfma_f32_16x16x32_bf16 v[74:77], v[240:243], v[8:11], v[74:77]
	ds_read_b128 v[240:243], v203 offset:128
	s_waitcnt lgkmcnt(6)
	v_mfma_f32_16x16x32_bf16 v[78:81], v[244:247], v[8:11], v[78:81]
	ds_read_b128 v[244:247], v203 offset:4480
	s_waitcnt lgkmcnt(6)
	v_mfma_f32_16x16x32_bf16 v[82:85], v[248:251], v[8:11], v[82:85]
	ds_read_b128 v[248:251], v203 offset:8832
	s_waitcnt lgkmcnt(6)
	v_mfma_f32_16x16x32_bf16 v[86:89], v[224:227], v[8:11], v[86:89]
	ds_read_b128 v[224:227], v204 offset:128
	s_waitcnt lgkmcnt(6)
	v_mfma_f32_16x16x32_bf16 v[170:173], v[228:231], v[8:11], v[170:173]
	ds_read_b128 v[228:231], v203 offset:17536
	s_waitcnt lgkmcnt(6)
	v_mfma_f32_16x16x32_bf16 v[216:219], v[232:235], v[8:11], v[216:219]
	ds_read_b128 v[232:235], v203 offset:21888
	s_waitcnt lgkmcnt(6)
	v_mfma_f32_16x16x32_bf16 v[220:223], v[236:239], v[8:11], v[220:223]
	ds_read_b128 v[236:239], v203 offset:26240
	s_waitcnt lgkmcnt(6)
	v_mfma_f32_16x16x32_bf16 v[90:93], v[240:243], v[4:7], v[90:93]
	ds_read_b128 v[240:243], v205 offset:128
	s_waitcnt lgkmcnt(6)
	v_mfma_f32_16x16x32_bf16 v[162:165], v[244:247], v[4:7], v[162:165]
	ds_read_b128 v[244:247], v203 offset:34944
	s_waitcnt lgkmcnt(6)
	v_mfma_f32_16x16x32_bf16 v[166:169], v[248:251], v[4:7], v[166:169]
	ds_read_b128 v[248:251], v203 offset:39296
	s_waitcnt lgkmcnt(6)
	v_mfma_f32_16x16x32_bf16 v[48:51], v[224:227], v[4:7], v[48:51]
	ds_read_b128 v[224:227], v203 offset:43648
	s_waitcnt lgkmcnt(6)
	v_mfma_f32_16x16x32_bf16 v[54:57], v[228:231], v[4:7], v[54:57]
	ds_read_b128 v[228:231], v206 offset:128
	s_waitcnt lgkmcnt(6)
	v_mfma_f32_16x16x32_bf16 v[58:61], v[232:235], v[4:7], v[58:61]
	ds_read_b128 v[232:235], v203 offset:52352
	s_waitcnt lgkmcnt(6)
	v_mfma_f32_16x16x32_bf16 v[62:65], v[236:239], v[4:7], v[62:65]
	ds_read_b128 v[236:239], v203 offset:56704
	s_waitcnt lgkmcnt(6)
	v_mfma_f32_16x16x32_bf16 v[66:69], v[240:243], v[4:7], v[66:69]
	ds_read_b128 v[240:243], v203 offset:61056
	s_waitcnt lgkmcnt(6)
	v_mfma_f32_16x16x32_bf16 v[70:73], v[244:247], v[4:7], v[70:73]
	ds_read_b128 v[244:247], v207 offset:128
	s_waitcnt lgkmcnt(6)
	v_mfma_f32_16x16x32_bf16 v[74:77], v[248:251], v[4:7], v[74:77]
	ds_read_b128 v[248:251], v203 offset:192
	s_waitcnt lgkmcnt(6)
	v_mfma_f32_16x16x32_bf16 v[78:81], v[224:227], v[4:7], v[78:81]
	ds_read_b128 v[224:227], v203 offset:4544
	s_waitcnt lgkmcnt(6)
	v_mfma_f32_16x16x32_bf16 v[82:85], v[228:231], v[4:7], v[82:85]
	ds_read_b128 v[228:231], v203 offset:8896
	s_waitcnt lgkmcnt(6)
	v_mfma_f32_16x16x32_bf16 v[86:89], v[232:235], v[4:7], v[86:89]
	ds_read_b128 v[232:235], v204 offset:192
	s_waitcnt lgkmcnt(6)
	v_mfma_f32_16x16x32_bf16 v[170:173], v[236:239], v[4:7], v[170:173]
	ds_read_b128 v[236:239], v203 offset:17600
	s_waitcnt lgkmcnt(6)
	v_mfma_f32_16x16x32_bf16 v[216:219], v[240:243], v[4:7], v[216:219]
	ds_read_b128 v[240:243], v203 offset:21952
	s_waitcnt lgkmcnt(6)
	v_mfma_f32_16x16x32_bf16 v[220:223], v[244:247], v[4:7], v[220:223]
	ds_read_b128 v[244:247], v203 offset:26304
	s_waitcnt lgkmcnt(6)
	v_mfma_f32_16x16x32_bf16 v[90:93], v[248:251], v[0:3], v[90:93]
	ds_read_b128 v[248:251], v205 offset:192
	s_waitcnt lgkmcnt(6)
	v_mfma_f32_16x16x32_bf16 v[162:165], v[224:227], v[0:3], v[162:165]
	ds_read_b128 v[224:227], v203 offset:35008
	s_waitcnt lgkmcnt(6)
	v_mfma_f32_16x16x32_bf16 v[166:169], v[228:231], v[0:3], v[166:169]
	ds_read_b128 v[228:231], v203 offset:39360
	s_waitcnt lgkmcnt(6)
	v_mfma_f32_16x16x32_bf16 v[48:51], v[232:235], v[0:3], v[48:51]
	ds_read_b128 v[232:235], v203 offset:43712
	s_waitcnt lgkmcnt(6)
	v_mfma_f32_16x16x32_bf16 v[54:57], v[236:239], v[0:3], v[54:57]
	ds_read_b128 v[236:239], v206 offset:192
	s_waitcnt lgkmcnt(6)
	v_mfma_f32_16x16x32_bf16 v[58:61], v[240:243], v[0:3], v[58:61]
	ds_read_b128 v[240:243], v203 offset:52416
	s_waitcnt lgkmcnt(6)
	v_mfma_f32_16x16x32_bf16 v[62:65], v[244:247], v[0:3], v[62:65]
	ds_read_b128 v[244:247], v203 offset:56768
	s_waitcnt lgkmcnt(6)
	v_mfma_f32_16x16x32_bf16 v[66:69], v[248:251], v[0:3], v[66:69]
	ds_read_b128 v[248:251], v203 offset:61120
	s_waitcnt lgkmcnt(6)
	v_mfma_f32_16x16x32_bf16 v[70:73], v[224:227], v[0:3], v[70:73]
	ds_read_b128 v[224:227], v207 offset:192
	s_waitcnt lgkmcnt(6)
	v_mfma_f32_16x16x32_bf16 v[74:77], v[228:231], v[0:3], v[74:77]
	s_waitcnt lgkmcnt(5)
	v_mfma_f32_16x16x32_bf16 v[78:81], v[232:235], v[0:3], v[78:81]
	s_waitcnt lgkmcnt(4)
	v_mfma_f32_16x16x32_bf16 v[82:85], v[236:239], v[0:3], v[82:85]
	s_waitcnt lgkmcnt(3)
	v_mfma_f32_16x16x32_bf16 v[86:89], v[240:243], v[0:3], v[86:89]
	s_waitcnt lgkmcnt(2)
	v_mfma_f32_16x16x32_bf16 v[170:173], v[244:247], v[0:3], v[170:173]
	s_waitcnt lgkmcnt(1)
	v_mfma_f32_16x16x32_bf16 v[216:219], v[248:251], v[0:3], v[216:219]
	s_waitcnt lgkmcnt(0)
	v_mfma_f32_16x16x32_bf16 v[220:223], v[224:227], v[0:3], v[220:223]
	s_nop 7
	v_mov_b32_e32 v44, v54
	v_mov_b32_e32 v45, v55
	v_mov_b32_e32 v46, v56
	v_mov_b32_e32 v47, v57
	v_mov_b32_e32 v40, v58
	v_mov_b32_e32 v41, v59
	v_mov_b32_e32 v42, v60
	v_mov_b32_e32 v43, v61
	v_mov_b32_e32 v36, v62
	v_mov_b32_e32 v37, v63
	v_mov_b32_e32 v38, v64
	v_mov_b32_e32 v39, v65
	v_mov_b32_e32 v32, v66
	v_mov_b32_e32 v33, v67
	v_mov_b32_e32 v34, v68
	v_mov_b32_e32 v35, v69
	v_mov_b32_e32 v28, v70
	v_mov_b32_e32 v29, v71
	v_mov_b32_e32 v30, v72
	v_mov_b32_e32 v31, v73
	v_mov_b32_e32 v24, v74
	v_mov_b32_e32 v25, v75
	v_mov_b32_e32 v26, v76
	v_mov_b32_e32 v27, v77
	v_mov_b32_e32 v20, v78
	v_mov_b32_e32 v21, v79
	v_mov_b32_e32 v22, v80
	v_mov_b32_e32 v23, v81
	v_mov_b32_e32 v16, v82
	v_mov_b32_e32 v17, v83
	v_mov_b32_e32 v18, v84
	v_mov_b32_e32 v19, v85
	v_mov_b32_e32 v12, v86
	v_mov_b32_e32 v13, v87
	v_mov_b32_e32 v14, v88
	v_mov_b32_e32 v15, v89
	v_mov_b32_e32 v8, v170
	v_mov_b32_e32 v9, v171
	v_mov_b32_e32 v10, v172
	v_mov_b32_e32 v11, v173
	v_mov_b32_e32 v4, v216
	v_mov_b32_e32 v5, v217
	v_mov_b32_e32 v6, v218
	v_mov_b32_e32 v7, v219
	v_mov_b32_e32 v0, v220
	v_mov_b32_e32 v1, v221
	v_mov_b32_e32 v2, v222
	v_mov_b32_e32 v3, v223
	v_max_f32_e32 v54, v93, v93
	v_max_f32_e32 v55, v92, v92
	v_max_f32_e32 v54, v55, v54
	v_max_f32_e32 v55, v165, v165
	v_max_f32_e32 v56, v164, v164
	v_max_f32_e32 v55, v56, v55
	v_max3_f32 v54, v90, v91, v54
	v_max3_f32 v55, v162, v163, v55
	s_mov_b32 s0, 0xff800000
	v_max3_f32 v54, v54, s0, v55
	v_max_f32_e32 v55, v169, v169
	v_max_f32_e32 v56, v168, v168
	v_max_f32_e32 v55, v56, v55
	v_max_f32_e32 v56, v51, v51
	v_max_f32_e32 v57, v50, v50
	v_max_f32_e32 v56, v57, v56
	v_max3_f32 v55, v166, v167, v55
	v_max3_f32 v56, v48, v49, v56
	v_max3_f32 v54, v54, v55, v56
	v_max_f32_e32 v55, v47, v47
	v_max_f32_e32 v56, v46, v46
	v_max_f32_e32 v55, v56, v55
	v_max_f32_e32 v56, v43, v43
	v_max_f32_e32 v57, v42, v42
	v_max_f32_e32 v56, v57, v56
	v_max3_f32 v55, v44, v45, v55
	v_max3_f32 v56, v40, v41, v56
	v_max3_f32 v54, v54, v55, v56
	v_max_f32_e32 v55, v39, v39
	v_max_f32_e32 v56, v38, v38
	v_max_f32_e32 v55, v56, v55
	v_max_f32_e32 v56, v35, v35
	v_max_f32_e32 v57, v34, v34
	v_max_f32_e32 v56, v57, v56
	v_max3_f32 v55, v36, v37, v55
	v_max3_f32 v56, v32, v33, v56
	v_max3_f32 v54, v54, v55, v56
	v_max_f32_e32 v55, v31, v31
	v_max_f32_e32 v56, v30, v30
	v_max_f32_e32 v55, v56, v55
	v_max_f32_e32 v56, v27, v27
	v_max_f32_e32 v57, v26, v26
	v_max_f32_e32 v56, v57, v56
	v_max3_f32 v55, v28, v29, v55
	v_max3_f32 v56, v24, v25, v56
	v_max3_f32 v54, v54, v55, v56
	v_max_f32_e32 v55, v23, v23
	v_max_f32_e32 v56, v22, v22
	v_max_f32_e32 v55, v56, v55
	v_max_f32_e32 v56, v19, v19
	v_max_f32_e32 v57, v18, v18
	v_max_f32_e32 v56, v57, v56
	v_max3_f32 v55, v20, v21, v55
	v_max3_f32 v56, v16, v17, v56
	v_max3_f32 v54, v54, v55, v56
	v_max_f32_e32 v55, v15, v15
	v_max_f32_e32 v56, v14, v14
	v_max_f32_e32 v55, v56, v55
	v_max_f32_e32 v56, v11, v11
	v_max_f32_e32 v57, v10, v10
	v_max_f32_e32 v56, v57, v56
	v_max3_f32 v55, v12, v13, v55
	v_max3_f32 v56, v8, v9, v56
	v_max3_f32 v54, v54, v55, v56
	v_max_f32_e32 v55, v7, v7
	v_max_f32_e32 v56, v6, v6
	v_max_f32_e32 v55, v56, v55
	v_max_f32_e32 v56, v3, v3
	v_max_f32_e32 v57, v2, v2
	v_max_f32_e32 v56, v57, v56
	v_max3_f32 v55, v4, v5, v55
	v_max3_f32 v56, v0, v1, v56
	v_max3_f32 v54, v54, v55, v56
	v_and_b32_e32 v56, 64, v188
	v_xor_b32_e32 v55, 16, v188
	v_add_u32_e32 v56, 64, v56
	v_cmp_lt_i32_e32 vcc, v55, v56
	s_barrier
	s_nop 0
	v_cndmask_b32_e32 v55, v188, v55, vcc
	v_lshlrev_b32_e32 v58, 2, v55
	ds_bpermute_b32 v55, v58, v54
	s_waitcnt lgkmcnt(0)
	v_lshlrev_b32_e32 v152, 1, v98
	s_mov_b64 s[22:23], 0
	s_mov_b64 s[24:25], -1
	v_max_f32_e32 v55, v55, v55
	v_max_f32_e32 v54, v54, v55
	v_xor_b32_e32 v55, 32, v188
	v_cmp_lt_i32_e32 vcc, v55, v56
	s_nop 1
	v_cndmask_b32_e32 v55, v188, v55, vcc
	v_lshlrev_b32_e32 v59, 2, v55
	ds_bpermute_b32 v55, v59, v54
	s_waitcnt lgkmcnt(0)
	v_max_f32_e32 v55, v55, v55
	v_max_f32_e32 v60, v54, v55
	v_sub_f32_e32 v54, v90, v60
	v_mul_f32_e32 v54, 0x3fb8aa3b, v54
	v_sub_f32_e32 v55, v91, v60
	v_exp_f32_e32 v54, v54
	v_mul_f32_e32 v55, 0x3fb8aa3b, v55
	v_sub_f32_e32 v56, v92, v60
	v_sub_f32_e32 v57, v93, v60
	v_exp_f32_e32 v55, v55
	v_mul_f32_e32 v56, 0x3fb8aa3b, v56
	v_mul_f32_e32 v57, 0x3fb8aa3b, v57
	v_exp_f32_e32 v56, v56
	v_exp_f32_e32 v57, v57
	v_add_f32_e32 v61, 0, v54
	v_add_f32_e32 v61, v55, v61
	v_add_f32_e32 v61, v56, v61
	v_cvt_pk_bf16_f32 v54, v54, v55
	v_cvt_pk_bf16_f32 v55, v56, v57
	v_sub_f32_e32 v56, v162, v60
	v_add_f32_e32 v61, v57, v61
	v_mul_f32_e32 v56, 0x3fb8aa3b, v56
	v_sub_f32_e32 v57, v163, v60
	v_sub_f32_e32 v62, v164, v60
	v_sub_f32_e32 v63, v165, v60
	v_exp_f32_e32 v56, v56
	v_mul_f32_e32 v57, 0x3fb8aa3b, v57
	v_mul_f32_e32 v62, 0x3fb8aa3b, v62
	v_mul_f32_e32 v63, 0x3fb8aa3b, v63
	v_exp_f32_e32 v57, v57
	v_exp_f32_e32 v62, v62
	v_exp_f32_e32 v63, v63
	v_add_f32_e32 v61, v56, v61
	v_add_f32_e32 v61, v57, v61
	v_cvt_pk_bf16_f32 v56, v56, v57
	v_cvt_pk_bf16_f32 v57, v62, v63
	ds_write2_b64 v215, v[54:55], v[56:57] offset1:4
	v_sub_f32_e32 v54, v166, v60
	v_mul_f32_e32 v54, 0x3fb8aa3b, v54
	v_sub_f32_e32 v55, v167, v60
	v_exp_f32_e32 v54, v54
	v_mul_f32_e32 v55, 0x3fb8aa3b, v55
	v_sub_f32_e32 v56, v168, v60
	v_exp_f32_e32 v55, v55
	v_mul_f32_e32 v56, 0x3fb8aa3b, v56
	v_sub_f32_e32 v57, v169, v60
	v_add_f32_e32 v61, v62, v61
	v_exp_f32_e32 v56, v56
	v_mul_f32_e32 v57, 0x3fb8aa3b, v57
	v_sub_f32_e32 v48, v48, v60
	v_add_f32_e32 v61, v63, v61
	v_exp_f32_e32 v57, v57
	v_mul_f32_e32 v48, 0x3fb8aa3b, v48
	v_sub_f32_e32 v49, v49, v60
	v_add_f32_e32 v61, v54, v61
	v_exp_f32_e32 v48, v48
	v_mul_f32_e32 v49, 0x3fb8aa3b, v49
	v_sub_f32_e32 v50, v50, v60
	v_add_f32_e32 v61, v55, v61
	v_exp_f32_e32 v49, v49
	v_mul_f32_e32 v50, 0x3fb8aa3b, v50
	v_sub_f32_e32 v51, v51, v60
	v_add_f32_e32 v61, v56, v61
	v_exp_f32_e32 v50, v50
	v_mul_f32_e32 v51, 0x3fb8aa3b, v51
	v_sub_f32_e32 v44, v44, v60
	v_add_f32_e32 v61, v57, v61
	v_exp_f32_e32 v51, v51
	v_mul_f32_e32 v44, 0x3fb8aa3b, v44
	v_sub_f32_e32 v45, v45, v60
	v_cvt_pk_bf16_f32 v54, v54, v55
	v_cvt_pk_bf16_f32 v55, v56, v57
	v_add_f32_e32 v56, v48, v61
	v_exp_f32_e32 v44, v44
	v_mul_f32_e32 v45, 0x3fb8aa3b, v45
	v_sub_f32_e32 v46, v46, v60
	v_add_f32_e32 v56, v49, v56
	v_exp_f32_e32 v45, v45
	v_mul_f32_e32 v46, 0x3fb8aa3b, v46
	v_sub_f32_e32 v47, v47, v60
	v_add_f32_e32 v56, v50, v56
	v_exp_f32_e32 v46, v46
	v_mul_f32_e32 v47, 0x3fb8aa3b, v47
	v_sub_f32_e32 v40, v40, v60
	v_add_f32_e32 v56, v51, v56
	v_cvt_pk_bf16_f32 v48, v48, v49
	v_cvt_pk_bf16_f32 v49, v50, v51
	v_exp_f32_e32 v47, v47
	v_mul_f32_e32 v40, 0x3fb8aa3b, v40
	v_sub_f32_e32 v41, v41, v60
	ds_write2_b64 v215, v[54:55], v[48:49] offset0:8 offset1:12
	v_add_f32_e32 v48, v44, v56
	v_exp_f32_e32 v40, v40
	v_mul_f32_e32 v41, 0x3fb8aa3b, v41
	v_sub_f32_e32 v42, v42, v60
	v_add_f32_e32 v48, v45, v48
	v_exp_f32_e32 v41, v41
	v_mul_f32_e32 v42, 0x3fb8aa3b, v42
	v_sub_f32_e32 v43, v43, v60
	v_add_f32_e32 v48, v46, v48
	v_exp_f32_e32 v42, v42
	v_mul_f32_e32 v43, 0x3fb8aa3b, v43
	v_sub_f32_e32 v36, v36, v60
	v_add_f32_e32 v48, v47, v48
	v_exp_f32_e32 v43, v43
	v_mul_f32_e32 v36, 0x3fb8aa3b, v36
	v_sub_f32_e32 v37, v37, v60
	v_cvt_pk_bf16_f32 v44, v44, v45
	v_cvt_pk_bf16_f32 v45, v46, v47
	v_add_f32_e32 v46, v40, v48
	v_exp_f32_e32 v36, v36
	v_mul_f32_e32 v37, 0x3fb8aa3b, v37
	v_sub_f32_e32 v38, v38, v60
	v_add_f32_e32 v46, v41, v46
	v_exp_f32_e32 v37, v37
	v_mul_f32_e32 v38, 0x3fb8aa3b, v38
	v_sub_f32_e32 v39, v39, v60
	v_add_f32_e32 v46, v42, v46
	v_exp_f32_e32 v38, v38
	v_mul_f32_e32 v39, 0x3fb8aa3b, v39
	v_sub_f32_e32 v32, v32, v60
	v_add_f32_e32 v46, v43, v46
	v_cvt_pk_bf16_f32 v40, v40, v41
	v_cvt_pk_bf16_f32 v41, v42, v43
	v_exp_f32_e32 v39, v39
	v_mul_f32_e32 v32, 0x3fb8aa3b, v32
	v_sub_f32_e32 v33, v33, v60
	ds_write2_b64 v215, v[44:45], v[40:41] offset0:16 offset1:20
	v_add_f32_e32 v40, v36, v46
	v_exp_f32_e32 v32, v32
	v_mul_f32_e32 v33, 0x3fb8aa3b, v33
	v_sub_f32_e32 v34, v34, v60
	v_add_f32_e32 v40, v37, v40
	v_exp_f32_e32 v33, v33
	v_mul_f32_e32 v34, 0x3fb8aa3b, v34
	v_sub_f32_e32 v35, v35, v60
	v_add_f32_e32 v40, v38, v40
	v_exp_f32_e32 v34, v34
	v_mul_f32_e32 v35, 0x3fb8aa3b, v35
	v_sub_f32_e32 v28, v28, v60
	v_add_f32_e32 v40, v39, v40
	v_exp_f32_e32 v35, v35
	v_mul_f32_e32 v28, 0x3fb8aa3b, v28
	v_sub_f32_e32 v29, v29, v60
	v_cvt_pk_bf16_f32 v36, v36, v37
	v_cvt_pk_bf16_f32 v37, v38, v39
	v_add_f32_e32 v38, v32, v40
	v_exp_f32_e32 v28, v28
	v_mul_f32_e32 v29, 0x3fb8aa3b, v29
	v_sub_f32_e32 v30, v30, v60
	v_add_f32_e32 v38, v33, v38
	v_exp_f32_e32 v29, v29
	v_mul_f32_e32 v30, 0x3fb8aa3b, v30
	v_sub_f32_e32 v31, v31, v60
	v_add_f32_e32 v38, v34, v38
	v_exp_f32_e32 v30, v30
	v_mul_f32_e32 v31, 0x3fb8aa3b, v31
	v_sub_f32_e32 v24, v24, v60
	v_add_f32_e32 v38, v35, v38
	v_cvt_pk_bf16_f32 v32, v32, v33
	v_cvt_pk_bf16_f32 v33, v34, v35
	v_exp_f32_e32 v31, v31
	v_mul_f32_e32 v24, 0x3fb8aa3b, v24
	v_sub_f32_e32 v25, v25, v60
	ds_write2_b64 v215, v[36:37], v[32:33] offset0:24 offset1:28
	v_add_f32_e32 v32, v28, v38
	v_exp_f32_e32 v24, v24
	v_mul_f32_e32 v25, 0x3fb8aa3b, v25
	v_sub_f32_e32 v26, v26, v60
	v_add_f32_e32 v32, v29, v32
	v_exp_f32_e32 v25, v25
	v_mul_f32_e32 v26, 0x3fb8aa3b, v26
	v_sub_f32_e32 v27, v27, v60
	v_add_f32_e32 v32, v30, v32
	v_exp_f32_e32 v26, v26
	v_mul_f32_e32 v27, 0x3fb8aa3b, v27
	v_sub_f32_e32 v20, v20, v60
	v_add_f32_e32 v32, v31, v32
	v_exp_f32_e32 v27, v27
	v_mul_f32_e32 v20, 0x3fb8aa3b, v20
	v_sub_f32_e32 v21, v21, v60
	v_cvt_pk_bf16_f32 v28, v28, v29
	v_cvt_pk_bf16_f32 v29, v30, v31
	v_add_f32_e32 v30, v24, v32
	v_exp_f32_e32 v20, v20
	v_mul_f32_e32 v21, 0x3fb8aa3b, v21
	v_sub_f32_e32 v22, v22, v60
	v_add_f32_e32 v30, v25, v30
	v_exp_f32_e32 v21, v21
	v_mul_f32_e32 v22, 0x3fb8aa3b, v22
	v_sub_f32_e32 v23, v23, v60
	v_add_f32_e32 v30, v26, v30
	v_exp_f32_e32 v22, v22
	v_mul_f32_e32 v23, 0x3fb8aa3b, v23
	v_sub_f32_e32 v16, v16, v60
	v_add_f32_e32 v30, v27, v30
	v_cvt_pk_bf16_f32 v24, v24, v25
	v_cvt_pk_bf16_f32 v25, v26, v27
	v_exp_f32_e32 v23, v23
	v_mul_f32_e32 v16, 0x3fb8aa3b, v16
	v_sub_f32_e32 v17, v17, v60
	ds_write2_b64 v215, v[28:29], v[24:25] offset0:32 offset1:36
	v_add_f32_e32 v24, v20, v30
	v_exp_f32_e32 v16, v16
	v_mul_f32_e32 v17, 0x3fb8aa3b, v17
	v_sub_f32_e32 v18, v18, v60
	v_add_f32_e32 v24, v21, v24
	v_exp_f32_e32 v17, v17
	v_mul_f32_e32 v18, 0x3fb8aa3b, v18
	v_sub_f32_e32 v19, v19, v60
	v_add_f32_e32 v24, v22, v24
	v_exp_f32_e32 v18, v18
	v_mul_f32_e32 v19, 0x3fb8aa3b, v19
	v_sub_f32_e32 v12, v12, v60
	v_add_f32_e32 v24, v23, v24
	v_exp_f32_e32 v19, v19
	v_mul_f32_e32 v12, 0x3fb8aa3b, v12
	v_sub_f32_e32 v13, v13, v60
	v_cvt_pk_bf16_f32 v20, v20, v21
	v_cvt_pk_bf16_f32 v21, v22, v23
	v_add_f32_e32 v22, v16, v24
	v_exp_f32_e32 v12, v12
	v_mul_f32_e32 v13, 0x3fb8aa3b, v13
	v_sub_f32_e32 v14, v14, v60
	v_add_f32_e32 v22, v17, v22
	v_exp_f32_e32 v13, v13
	v_mul_f32_e32 v14, 0x3fb8aa3b, v14
	v_sub_f32_e32 v15, v15, v60
	v_add_f32_e32 v22, v18, v22
	v_exp_f32_e32 v14, v14
	v_mul_f32_e32 v15, 0x3fb8aa3b, v15
	v_sub_f32_e32 v8, v8, v60
	v_add_f32_e32 v22, v19, v22
	v_cvt_pk_bf16_f32 v16, v16, v17
	v_cvt_pk_bf16_f32 v17, v18, v19
	v_exp_f32_e32 v15, v15
	v_mul_f32_e32 v8, 0x3fb8aa3b, v8
	v_sub_f32_e32 v9, v9, v60
	ds_write2_b64 v215, v[20:21], v[16:17] offset0:40 offset1:44
	v_add_f32_e32 v16, v12, v22
	v_exp_f32_e32 v8, v8
	v_mul_f32_e32 v9, 0x3fb8aa3b, v9
	v_sub_f32_e32 v10, v10, v60
	v_add_f32_e32 v16, v13, v16
	v_exp_f32_e32 v9, v9
	v_mul_f32_e32 v10, 0x3fb8aa3b, v10
	v_sub_f32_e32 v11, v11, v60
	v_add_f32_e32 v16, v14, v16
	v_exp_f32_e32 v10, v10
	v_mul_f32_e32 v11, 0x3fb8aa3b, v11
	v_sub_f32_e32 v4, v4, v60
	v_add_f32_e32 v16, v15, v16
	v_exp_f32_e32 v11, v11
	v_mul_f32_e32 v4, 0x3fb8aa3b, v4
	v_sub_f32_e32 v5, v5, v60
	v_sub_f32_e32 v0, v0, v60
	v_cvt_pk_bf16_f32 v12, v12, v13
	v_add_f32_e32 v13, v8, v16
	v_exp_f32_e32 v4, v4
	v_mul_f32_e32 v5, 0x3fb8aa3b, v5
	v_sub_f32_e32 v6, v6, v60
	v_mul_f32_e32 v0, 0x3fb8aa3b, v0
	v_add_f32_e32 v13, v9, v13
	v_exp_f32_e32 v5, v5
	v_mul_f32_e32 v6, 0x3fb8aa3b, v6
	v_sub_f32_e32 v7, v7, v60
	v_exp_f32_e32 v16, v0
	v_sub_f32_e32 v0, v1, v60
	v_add_f32_e32 v13, v10, v13
	v_exp_f32_e32 v6, v6
	v_mul_f32_e32 v7, 0x3fb8aa3b, v7
	v_mul_f32_e32 v0, 0x3fb8aa3b, v0
	v_add_f32_e32 v13, v11, v13
	v_exp_f32_e32 v7, v7
	v_exp_f32_e32 v17, v0
	v_sub_f32_e32 v0, v2, v60
	v_add_f32_e32 v13, v4, v13
	v_mul_f32_e32 v0, 0x3fb8aa3b, v0
	v_add_f32_e32 v13, v5, v13
	v_exp_f32_e32 v18, v0
	v_sub_f32_e32 v0, v3, v60
	v_add_f32_e32 v13, v6, v13
	v_mul_f32_e32 v0, 0x3fb8aa3b, v0
	v_add_f32_e32 v13, v7, v13
	v_exp_f32_e32 v3, v0
	v_add_f32_e32 v0, v16, v13
	v_add_f32_e32 v0, v17, v0
	v_add_f32_e32 v0, v18, v0
	v_add_f32_e32 v2, v3, v0
	ds_bpermute_b32 v19, v58, v2
	v_cvt_pk_bf16_f32 v13, v14, v15
	v_cvt_pk_bf16_f32 v0, v8, v9
	v_cvt_pk_bf16_f32 v1, v10, v11
	ds_write2_b64 v215, v[12:13], v[0:1] offset0:48 offset1:52
	s_waitcnt lgkmcnt(1)
	v_add_f32_e32 v2, v2, v19
	ds_bpermute_b32 v8, v59, v2
	v_sub_f32_e32 v0, 0xff800000, v60
	v_mul_f32_e32 v0, 0x3fb8aa3b, v0
	v_exp_f32_e32 v9, v0
	v_cvt_pk_bf16_f32 v0, v4, v5
	s_waitcnt lgkmcnt(0)
	v_add_f32_e32 v2, v2, v8
	v_cvt_pk_bf16_f32 v1, v6, v7
	v_add_f32_e32 v4, v9, v2
	v_div_scale_f32 v5, s[20:21], v4, v4, 1.0
	v_rcp_f32_e32 v6, v5
	v_cvt_pk_bf16_f32 v2, v16, v17
	v_cvt_pk_bf16_f32 v3, v18, v3
	ds_write2_b64 v215, v[0:1], v[2:3] offset0:56 offset1:60
	v_fma_f32 v0, -v5, v6, 1.0
	v_fmac_f32_e32 v6, v0, v6
	v_div_scale_f32 v0, vcc, 1.0, v4, 1.0
	v_mul_f32_e32 v1, v0, v6
	v_fma_f32 v2, -v5, v1, v0
	v_fmac_f32_e32 v1, v2, v6
	v_fma_f32 v0, -v5, v1, v0
	v_div_fmas_f32 v0, v0, v6, v1
	v_div_fixup_f32 v32, v0, v4, 1.0
	v_lshl_add_u64 v[0:1], v[52:53], 0, v[152:153]
	s_mov_b64 s[20:21], 0x17100000
	v_lshl_add_u64 v[34:35], v[0:1], 0, s[20:21]
	v_mov_b32_e32 v33, v32
